# same as previous but tile-step per XCD class computed for any grid size (no multiple-of-8 assumption)
# speedup vs baseline: 1.0412x; 1.0043x over previous
.LBB0_115:
	s_or_b64 exec, exec, s[0:1]
	v_mov_b32_e32 v78, v148
	s_mov_b32 s12, s55
	s_barrier
	s_mov_b32 s13, s94
	s_cmpk_gt_i32 s12, 0x2ad1
	s_cbranch_scc1 .LBB0_171
	v_ashrrev_i32_e32 v4, 2, v78
	v_lshlrev_b32_e32 v0, 5, v4
	v_ashrrev_i32_e32 v1, 31, v0
	v_lshlrev_b32_e32 v5, 4, v78
	v_lshlrev_b64 v[0:1], 1, v[0:1]
	v_and_b32_e32 v64, 48, v5
	v_mov_b32_e32 v65, 0
	s_movk_i32 s2, 0x50
	v_lshl_add_u64 v[2:3], s[44:45], 0, v[0:1]
	v_lshl_add_u64 v[0:1], s[48:49], 0, v[0:1]
	v_mad_u64_u32 v[70:71], s[0:1], v4, s2, v[64:65]
	v_lshl_add_u64 v[66:67], v[2:3], 0, v[64:65]
	v_lshl_add_u64 v[68:69], v[0:1], 0, v[64:65]
	v_lshrrev_b32_e32 v1, 1, v78
	v_and_b32_e32 v2, 31, v78
	s_mov_b32 s0, 0xfffffc0
	v_and_b32_e32 v0, 16, v1
	v_and_or_b32 v1, v1, s0, v2
	v_and_b32_e32 v2, 0x5f, v78
	v_mad_u64_u32 v[72:73], s[0:1], v1, s2, v[0:1]
	v_mad_u32_u24 v71, v2, s2, v0
	s_mov_b32 s3, 0
	s_movk_i32 s14, 0x2000
	s_movk_i32 s15, 0x4000
	s_movk_i32 s16, 0x6000
	s_mov_b32 s17, 0x8000
	s_mov_b32 s18, 0xa000
	s_mov_b32 s19, 0xc000
	s_mov_b32 s20, 0xe000
	s_mov_b32 s21, 0x10000
	s_mov_b32 s22, 0x12000
	s_mov_b32 s23, 0x14000
	s_mov_b32 s24, 0x16000
	s_mov_b32 s25, 0x18000
	s_mov_b32 s26, 0x1a000
	s_mov_b32 s27, 0x1c000
	s_mov_b32 s28, 0x1e000
	s_mov_b32 s29, 0x20000
	s_mov_b32 s30, 0x22000
	s_mov_b32 s31, 0x24000
	s_mov_b32 s33, 0x26000
	s_mov_b32 s34, 0x28000
	s_mov_b32 s35, 0x2a000
	s_mov_b32 s52, 0x2c000
	s_mov_b32 s53, 0x2e000
	s_mov_b32 s54, 0x30000
	s_mov_b32 s55, 0x32000
	s_mov_b32 s56, 0x34000
	s_mov_b32 s57, 0x36000
	s_mov_b32 s58, 0x38000
	s_mov_b32 s59, 0x3a000
	s_mov_b32 s60, 0x3c000
	s_mov_b32 s61, 0x3e000
	s_mov_b32 s62, 0x3f000
	s_movk_i32 s63, 0x110
	s_movk_i32 s64, 0x2a00
	s_movk_i32 s65, 0xe00
	v_and_b32_e32 v161, 63, v148
	v_lshrrev_b32_e32 v162, 6, v148
	v_and_b32_e32 v163, 31, v161
	v_lshlrev_b32_e32 v163, 6, v163
	v_lshrrev_b32_e32 v164, 5, v161
	v_bfe_u32 v165, v161, 2, 2
	v_xor_b32_e32 v164, v164, v165
	v_lshl_add_u32 v163, v164, 4, v163
	v_lshrrev_b32_e32 v164, 1, v162
	v_lshl_add_u32 v154, v164, 12, v163
	v_and_b32_e32 v164, 1, v162
	v_lshl_add_u32 v156, v164, 12, v163
	v_xor_b32_e32 v155, 32, v154
	v_xor_b32_e32 v157, 32, v156
	v_lshrrev_b32_e32 v163, 2, v161
	v_lshlrev_b32_e32 v163, 6, v163
	v_and_b32_e32 v164, 3, v161
	v_bfe_u32 v165, v161, 4, 2
	v_xor_b32_e32 v164, v164, v165
	v_lshl_add_u32 v163, v164, 4, v163
	v_lshl_add_u32 v160, v162, 11, v163
	v_readfirstlane_b32 s20, v162
	s_lshl_b32 s20, s20, 11
	s_and_b32 s25, s12, 7
	s_lshr_b32 s12, s12, 3
	s_add_u32 s26, s13, 7
	s_sub_u32 s26, s26, s25
	s_lshr_b32 s26, s26, 3
	s_sub_u32 s27, 268, s25
	s_lshr_b32 s27, s27, 3
	s_mul_i32 s27, s27, 21
	s_branch .Lg1a_hdr

.LBB0_118:
.Lg1a_ctl:
	s_cmp_eq_u32 s24, 0
	s_cbranch_scc1 .Lg1a_pass2
	s_add_i32 s12, s12, s26
	s_cmp_lt_u32 s12, s27
	s_cbranch_scc0 .LBB0_170
	s_branch .Lg1a_hdr

.LBB0_493:
	s_or_b64 exec, exec, s[2:3]
	s_add_u32 s0, s48, 0xa80000
	s_addc_u32 s1, s49, 0
	v_mov_b32_e32 v150, v148
	s_mov_b32 s4, s55
	s_waitcnt lgkmcnt(0)
	s_barrier
	v_writelane_b32 v158, s0, 24
	s_mov_b32 s5, s94
	s_cmpk_gt_i32 s4, 0x827
	v_writelane_b32 v158, s1, 25
	s_cbranch_scc1 .LBB0_522
	v_ashrrev_i32_e32 v151, 2, v150
	v_lshlrev_b32_e32 v0, 4, v150
	v_and_b32_e32 v128, 48, v0
	v_lshlrev_b32_e32 v0, 5, v151
	v_ashrrev_i32_e32 v1, 31, v0
	v_readlane_b32 s0, v158, 24
	v_mov_b32_e32 v131, 0
	v_lshlrev_b64 v[0:1], 1, v[0:1]
	v_readlane_b32 s1, v158, 25
	v_mov_b32_e32 v129, v131
	v_and_b32_e32 v5, 31, v150
	v_lshl_add_u64 v[2:3], s[0:1], 0, v[0:1]
	v_lshl_add_u64 v[134:135], v[2:3], 0, v[128:129]
	v_lshrrev_b32_e32 v3, 1, v150
	s_mov_b32 s1, 0xfffffc0
	s_movk_i32 s0, 0x50
	v_and_b32_e32 v4, 16, v3
	v_and_or_b32 v3, v3, s1, v5
	v_and_b32_e32 v5, 0x5f, v150
	v_mul_lo_u32 v2, v151, s0
	v_mul_lo_u32 v3, v3, s0
	v_mul_u32_u24_e32 v5, 0x50, v5
	s_add_u32 s0, s90, 0x22aa00
	v_lshl_add_u64 v[132:133], s[46:47], 0, v[128:129]
	s_addc_u32 s1, s91, 0
	v_lshl_add_u64 v[136:137], s[48:49], 0, v[0:1]
	s_movk_i32 s6, 0x2a00
	v_mov_b32_e32 v152, 0x60000
	s_mov_b32 s7, 0xa8000
	v_add_u32_e32 v153, v2, v128
	v_mov_b64_e32 v[138:139], s[46:47]
	v_add_u32_e32 v154, v4, v3
	v_add_u32_e32 v155, v4, v5
	s_movk_i32 s8, 0x210
	v_and_b32_e32 v76, 63, v148
	v_lshrrev_b32_e32 v77, 6, v148
	v_and_b32_e32 v130, 31, v76
	v_lshlrev_b32_e32 v130, 6, v130
	v_lshrrev_b32_e32 v64, 5, v76
	v_bfe_u32 v65, v76, 2, 2
	v_xor_b32_e32 v64, v64, v65
	v_lshl_add_u32 v130, v64, 4, v130
	v_lshrrev_b32_e32 v64, 1, v77
	v_lshl_add_u32 v151, v64, 12, v130
	v_and_b32_e32 v64, 1, v77
	v_lshl_add_u32 v157, v64, 12, v130
	v_xor_b32_e32 v156, 32, v151
	v_xor_b32_e32 v164, 32, v157
	v_lshrrev_b32_e32 v130, 2, v76
	v_lshlrev_b32_e32 v130, 6, v130
	v_and_b32_e32 v64, 3, v76
	v_bfe_u32 v65, v76, 4, 2
	v_xor_b32_e32 v64, v64, v65
	v_lshl_add_u32 v130, v64, 4, v130
	v_lshl_add_u32 v165, v77, 11, v130
	v_lshrrev_b32_e32 v130, 2, v76
	v_lshl_add_u32 v130, v77, 5, v130
	v_mul_u32_u24_e32 v130, 0x2a00, v130
	v_and_b32_e32 v64, 3, v76
	v_bfe_u32 v65, v76, 4, 2
	v_xor_b32_e32 v64, v64, v65
	v_lshl_add_u32 v166, v64, 4, v130
	v_add_u32_e32 v167, 0x2a000, v166
	v_readfirstlane_b32 s28, v77
	s_lshl_b32 s28, s28, 11
	s_and_b32 s33, s4, 7
	s_lshr_b32 s4, s4, 3
	s_add_u32 s56, s5, 7
	s_sub_u32 s56, s56, s33
	s_lshr_b32 s56, s56, 3
	s_sub_u32 s57, 268, s33
	s_lshr_b32 s57, s57, 3
	s_mul_i32 s57, s57, 4
	s_branch .Lg2a_hdr

.Lg2a_ctl:
	s_cmp_eq_u32 s32, 0
	s_cbranch_scc1 .Lg2a_pass2
	s_add_i32 s4, s4, s56
	s_cmp_lt_u32 s4, s57
	s_cbranch_scc0 .LBB0_522
	s_branch .Lg2a_hdr

.LBB0_566:
	s_or_b64 exec, exec, s[2:3]
	s_add_u32 s0, s48, 0xd80000
	s_addc_u32 s1, s49, 0
	v_mov_b32_e32 v80, v148
	s_mov_b32 s2, s55
	s_waitcnt lgkmcnt(0)
	s_barrier
	v_writelane_b32 v158, s0, 28
	s_mov_b32 s3, s94
	s_cmpk_gt_i32 s2, 0x2cdb
	v_writelane_b32 v158, s1, 29
	s_cbranch_scc1 .LBB0_570
	v_ashrrev_i32_e32 v4, 2, v80
	v_lshlrev_b32_e32 v0, 5, v4
	v_ashrrev_i32_e32 v1, 31, v0
	v_lshlrev_b32_e32 v5, 4, v80
	v_readlane_b32 s0, v158, 28
	v_lshlrev_b64 v[0:1], 1, v[0:1]
	v_and_b32_e32 v64, 48, v5
	v_mov_b32_e32 v65, 0
	v_readlane_b32 s1, v158, 29
	s_movk_i32 s4, 0x50
	v_lshl_add_u64 v[2:3], s[44:45], 0, v[0:1]
	v_lshl_add_u64 v[0:1], s[0:1], 0, v[0:1]
	v_mad_u64_u32 v[70:71], s[0:1], v4, s4, v[64:65]
	v_lshl_add_u64 v[66:67], v[2:3], 0, v[64:65]
	v_lshl_add_u64 v[68:69], v[0:1], 0, v[64:65]
	v_lshrrev_b32_e32 v1, 1, v80
	v_and_b32_e32 v2, 31, v80
	s_mov_b32 s0, 0xfffffc0
	v_and_b32_e32 v0, 16, v1
	v_and_or_b32 v1, v1, s0, v2
	v_and_b32_e32 v2, 0x5f, v80
	v_mad_u64_u32 v[72:73], s[0:1], v1, s4, v[0:1]
	v_mad_u32_u24 v71, v2, s4, v0
	s_add_u32 s4, s90, 0x22aa00
	s_mov_b32 s0, 0x358637bd
	s_addc_u32 s5, s91, 0
	s_movk_i32 s7, 0x2000
	s_movk_i32 s8, 0x4000
	s_movk_i32 s9, 0x6000
	s_mov_b32 s12, 0x8000
	s_mov_b32 s13, 0xa000
	s_mov_b32 s14, 0xc000
	s_mov_b32 s15, 0xe000
	s_mov_b32 s16, 0x10000
	s_mov_b32 s17, 0x12000
	s_mov_b32 s18, 0x14000
	s_mov_b32 s19, 0x16000
	s_mov_b32 s20, 0x18000
	s_mov_b32 s21, 0x1a000
	s_mov_b32 s22, 0x1c000
	s_mov_b32 s23, 0x1e000
	s_mov_b32 s24, 0x20000
	s_mov_b32 s25, 0x22000
	s_mov_b32 s26, 0x24000
	s_mov_b32 s27, 0x26000
	s_mov_b32 s28, 0x28000
	s_mov_b32 s29, 0x2a000
	s_mov_b32 s30, 0x2c000
	s_mov_b32 s31, 0x2e000
	s_mov_b32 s34, 0x30000
	s_mov_b32 s35, 0x32000
	s_mov_b32 s52, 0x34000
	s_mov_b32 s53, 0x36000
	s_mov_b32 s54, 0x38000
	s_mov_b32 s55, 0x3a000
	s_mov_b32 s56, 0x3c000
	s_mov_b32 s57, 0x3e000
	s_mov_b32 s58, 0x3f000
	s_movk_i32 s59, 0x90
	s_mov_b32 s6, 0x3a800000
	v_mov_b64_e32 v[74:75], s[0:1]
	s_mov_b32 s60, 0x800000
	s_movk_i32 s61, 0x58
	v_and_b32_e32 v146, 63, v148
	v_lshrrev_b32_e32 v147, 6, v148
	v_and_b32_e32 v165, 31, v146
	v_lshlrev_b32_e32 v165, 6, v165
	v_lshrrev_b32_e32 v166, 5, v146
	v_bfe_u32 v167, v146, 2, 2
	v_xor_b32_e32 v166, v166, v167
	v_lshl_add_u32 v165, v166, 4, v165
	v_lshrrev_b32_e32 v166, 1, v147
	v_lshl_add_u32 v160, v166, 12, v165
	v_and_b32_e32 v166, 1, v147
	v_lshl_add_u32 v162, v166, 12, v165
	v_xor_b32_e32 v161, 32, v160
	v_xor_b32_e32 v163, 32, v162
	v_lshrrev_b32_e32 v165, 2, v146
	v_lshlrev_b32_e32 v165, 6, v165
	v_and_b32_e32 v166, 3, v146
	v_bfe_u32 v167, v146, 4, 2
	v_xor_b32_e32 v166, v166, v167
	v_lshl_add_u32 v165, v166, 4, v165
	v_lshl_add_u32 v164, v147, 11, v165
	v_readfirstlane_b32 s20, v147
	s_lshl_b32 s20, s20, 11
	s_and_b32 s25, s2, 7
	s_lshr_b32 s2, s2, 3
	s_add_u32 s26, s3, 7
	s_sub_u32 s26, s26, s25
	s_lshr_b32 s26, s26, 3
	s_sub_u32 s27, 268, s25
	s_lshr_b32 s27, s27, 3
	s_mul_i32 s27, s27, 22
	s_branch .Lg3a_hdr

.Lg3a_ctl:
	s_cmp_eq_u32 s24, 0
	s_cbranch_scc1 .Lg3a_pass2
	s_add_i32 s2, s2, s26
	s_cmp_lt_u32 s2, s27
	s_cbranch_scc1 .Lg3a_hdr
	s_branch .Lg3a_exit

.LBB0_614:
	s_or_b64 exec, exec, s[2:3]
	s_add_u32 s0, s48, 0x1880000
	s_addc_u32 s1, s49, 0
	v_mov_b32_e32 v144, v148
	s_mov_b32 s8, s55
	s_waitcnt lgkmcnt(0)
	s_barrier
	v_writelane_b32 v158, s0, 26
	s_mov_b32 s9, s94
	s_cmpk_gt_i32 s8, 0x827
	v_writelane_b32 v158, s1, 27
	s_cbranch_scc1 .LBB0_637
	s_waitcnt vmcnt(0)
	v_ashrrev_i32_e32 v8, 2, v144
	v_lshlrev_b32_e32 v0, 5, v8
	v_ashrrev_i32_e32 v1, 31, v0
	v_lshlrev_b64 v[2:3], 1, v[0:1]
	v_lshlrev_b32_e32 v0, 4, v144
	v_and_b32_e32 v6, 48, v0
	v_mov_b32_e32 v0, 0
	v_readlane_b32 s0, v158, 26
	v_lshl_add_u64 v[4:5], s[46:47], 0, v[2:3]
	v_mov_b32_e32 v7, v0
	v_readlane_b32 s1, v158, 27
	v_lshl_add_u64 v[132:133], v[4:5], 0, v[6:7]
	v_mov_b32_e32 v145, 0xb0000
	v_lshl_add_u64 v[4:5], s[0:1], 0, v[2:3]
	v_lshl_add_u64 v[134:135], v[4:5], 0, v[6:7]
	v_lshrrev_b32_e32 v4, 1, v144
	v_and_b32_e32 v7, 31, v144
	s_mov_b32 s1, 0xfffffc0
	s_movk_i32 s0, 0x50
	v_and_b32_e32 v5, 16, v4
	v_and_or_b32 v4, v4, s1, v7
	v_and_b32_e32 v7, 0x5f, v144
	v_mul_lo_u32 v1, v8, s0
	v_mul_lo_u32 v4, v4, s0
	v_mul_u32_u24_e32 v7, 0x50, v7
	v_or_b32_e32 v2, v2, v6
	v_lshl_add_u64 v[136:137], s[48:49], 0, v[2:3]
	s_movk_i32 s10, 0x2000
	s_movk_i32 s11, 0x4000
	s_movk_i32 s12, 0x5000
	v_add_u32_e32 v146, v1, v6
	v_add_u32_e32 v147, v5, v4
	v_add_u32_e32 v150, v5, v7
	s_movk_i32 s13, 0x210
	v_and_b32_e32 v142, 63, v148
	v_lshrrev_b32_e32 v143, 6, v148
	v_and_b32_e32 v154, 31, v142
	v_lshlrev_b32_e32 v154, 6, v154
	v_lshrrev_b32_e32 v155, 5, v142
	v_bfe_u32 v156, v142, 2, 2
	v_xor_b32_e32 v155, v155, v156
	v_lshl_add_u32 v154, v155, 4, v154
	v_lshrrev_b32_e32 v155, 1, v143
	v_lshl_add_u32 v81, v155, 12, v154
	v_and_b32_e32 v155, 1, v143
	v_lshl_add_u32 v146, v155, 12, v154
	v_xor_b32_e32 v145, 32, v81
	v_xor_b32_e32 v147, 32, v146
	v_lshrrev_b32_e32 v154, 2, v142
	v_lshlrev_b32_e32 v154, 6, v154
	v_and_b32_e32 v155, 3, v142
	v_bfe_u32 v156, v142, 4, 2
	v_xor_b32_e32 v155, v155, v156
	v_lshl_add_u32 v154, v155, 4, v154
	v_lshl_add_u32 v157, v143, 11, v154
	v_readfirstlane_b32 s28, v143
	s_lshl_b32 s28, s28, 11
	s_and_b32 s33, s8, 7
	s_lshr_b32 s8, s8, 3
	s_add_u32 s56, s9, 7
	s_sub_u32 s56, s56, s33
	s_lshr_b32 s56, s56, 3
	s_sub_u32 s57, 268, s33
	s_lshr_b32 s57, s57, 3
	s_mul_i32 s57, s57, 4
	s_branch .Lg4a_hdr

.Lg4a_ctl:
	s_cmp_eq_u32 s32, 0
	s_cbranch_scc1 .Lg4a_pass2
	s_add_i32 s8, s8, s56
	s_cmp_lt_u32 s8, s57
	s_cbranch_scc1 .Lg4a_hdr
	s_branch .LBB0_637

.LBB0_818:
	s_or_b64 exec, exec, s[2:3]
	v_readlane_b32 s0, v158, 22
	s_waitcnt lgkmcnt(0)
	s_barrier
	v_readlane_b32 s1, v158, 23
	v_mov_b32_e32 v78, v148
	s_mov_b32 s12, s55
	v_writelane_b32 v158, s0, 22
	s_mov_b32 s13, s94
	s_cmpk_gt_i32 s12, 0x2ad1
	v_writelane_b32 v158, s1, 23
	s_cbranch_scc1 .LBB0_874
	v_ashrrev_i32_e32 v4, 2, v78
	v_lshlrev_b32_e32 v0, 5, v4
	v_ashrrev_i32_e32 v1, 31, v0
	v_lshlrev_b32_e32 v5, 4, v78
	v_lshlrev_b64 v[0:1], 1, v[0:1]
	v_and_b32_e32 v64, 48, v5
	v_mov_b32_e32 v65, 0
	s_movk_i32 s2, 0x50
	v_lshl_add_u64 v[2:3], s[44:45], 0, v[0:1]
	v_lshl_add_u64 v[0:1], s[48:49], 0, v[0:1]
	v_mad_u64_u32 v[70:71], s[0:1], v4, s2, v[64:65]
	v_lshl_add_u64 v[66:67], v[2:3], 0, v[64:65]
	v_lshl_add_u64 v[68:69], v[0:1], 0, v[64:65]
	v_lshrrev_b32_e32 v1, 1, v78
	v_and_b32_e32 v2, 31, v78
	s_mov_b32 s0, 0xfffffc0
	v_and_b32_e32 v0, 16, v1
	v_and_or_b32 v1, v1, s0, v2
	v_and_b32_e32 v2, 0x5f, v78
	v_mad_u64_u32 v[72:73], s[0:1], v1, s2, v[0:1]
	v_mad_u32_u24 v71, v2, s2, v0
	s_mov_b32 s3, 0
	s_movk_i32 s14, 0x2000
	s_movk_i32 s15, 0x4000
	s_movk_i32 s16, 0x6000
	s_mov_b32 s17, 0x8000
	s_mov_b32 s18, 0xa000
	s_mov_b32 s19, 0xc000
	s_mov_b32 s20, 0xe000
	s_mov_b32 s21, 0x10000
	s_mov_b32 s22, 0x12000
	s_mov_b32 s23, 0x14000
	s_mov_b32 s24, 0x16000
	s_mov_b32 s25, 0x18000
	s_mov_b32 s26, 0x1a000
	s_mov_b32 s27, 0x1c000
	s_mov_b32 s28, 0x1e000
	s_mov_b32 s29, 0x20000
	s_mov_b32 s30, 0x22000
	s_mov_b32 s31, 0x24000
	s_mov_b32 s33, 0x26000
	s_mov_b32 s34, 0x28000
	s_mov_b32 s35, 0x2a000
	s_mov_b32 s36, 0x2c000
	s_mov_b32 s37, 0x2e000
	s_mov_b32 s38, 0x30000
	s_mov_b32 s39, 0x32000
	s_mov_b32 s52, 0x34000
	s_mov_b32 s53, 0x36000
	s_mov_b32 s54, 0x38000
	s_mov_b32 s55, 0x3a000
	s_mov_b32 s56, 0x3c000
	s_mov_b32 s57, 0x3e000
	s_mov_b32 s58, 0x3f000
	s_movk_i32 s59, 0x110
	s_movk_i32 s60, 0x2a00
	s_movk_i32 s61, 0xe00
	v_and_b32_e32 v161, 63, v148
	v_lshrrev_b32_e32 v162, 6, v148
	v_and_b32_e32 v163, 31, v161
	v_lshlrev_b32_e32 v163, 6, v163
	v_lshrrev_b32_e32 v164, 5, v161
	v_bfe_u32 v165, v161, 2, 2
	v_xor_b32_e32 v164, v164, v165
	v_lshl_add_u32 v163, v164, 4, v163
	v_lshrrev_b32_e32 v164, 1, v162
	v_lshl_add_u32 v154, v164, 12, v163
	v_and_b32_e32 v164, 1, v162
	v_lshl_add_u32 v156, v164, 12, v163
	v_xor_b32_e32 v155, 32, v154
	v_xor_b32_e32 v157, 32, v156
	v_lshrrev_b32_e32 v163, 2, v161
	v_lshlrev_b32_e32 v163, 6, v163
	v_and_b32_e32 v164, 3, v161
	v_bfe_u32 v165, v161, 4, 2
	v_xor_b32_e32 v164, v164, v165
	v_lshl_add_u32 v163, v164, 4, v163
	v_lshl_add_u32 v160, v162, 11, v163
	v_readfirstlane_b32 s20, v162
	s_lshl_b32 s20, s20, 11
	s_and_b32 s25, s12, 7
	s_lshr_b32 s12, s12, 3
	s_add_u32 s26, s13, 7
	s_sub_u32 s26, s26, s25
	s_lshr_b32 s26, s26, 3
	s_sub_u32 s27, 268, s25
	s_lshr_b32 s27, s27, 3
	s_mul_i32 s27, s27, 21
	s_branch .Lg1b_hdr

.LBB0_1195:
	s_or_b64 exec, exec, s[2:3]
	v_mov_b32_e32 v150, v148
	s_mov_b32 s8, s55
	s_waitcnt lgkmcnt(0)
	s_barrier
	s_mov_b32 s9, s94
	s_cmpk_gt_i32 s8, 0x827
	s_cbranch_scc1 .LBB0_1224
	v_ashrrev_i32_e32 v151, 2, v150
	v_lshlrev_b32_e32 v0, 4, v150
	v_and_b32_e32 v128, 48, v0
	v_lshlrev_b32_e32 v0, 5, v151
	v_ashrrev_i32_e32 v1, 31, v0
	v_readlane_b32 s0, v158, 24
	v_mov_b32_e32 v131, 0
	v_lshlrev_b64 v[0:1], 1, v[0:1]
	v_readlane_b32 s1, v158, 25
	v_mov_b32_e32 v129, v131
	v_and_b32_e32 v5, 31, v150
	v_lshl_add_u64 v[2:3], s[0:1], 0, v[0:1]
	v_lshl_add_u64 v[134:135], v[2:3], 0, v[128:129]
	v_lshrrev_b32_e32 v3, 1, v150
	s_mov_b32 s1, 0xfffffc0
	s_movk_i32 s0, 0x50
	v_and_b32_e32 v4, 16, v3
	v_and_or_b32 v3, v3, s1, v5
	v_and_b32_e32 v5, 0x5f, v150
	v_mul_lo_u32 v2, v151, s0
	v_mul_lo_u32 v3, v3, s0
	v_mul_u32_u24_e32 v5, 0x50, v5
	s_add_u32 s0, s90, 0x22aa00
	v_lshl_add_u64 v[132:133], s[46:47], 0, v[128:129]
	s_addc_u32 s1, s91, 0
	v_lshl_add_u64 v[136:137], s[48:49], 0, v[0:1]
	s_movk_i32 s10, 0x2a00
	v_mov_b32_e32 v152, 0x60000
	s_mov_b32 s11, 0xa8000
	s_movk_i32 s12, 0x2000
	s_movk_i32 s13, 0x4000
	s_movk_i32 s14, 0x5000
	v_add_u32_e32 v153, v2, v128
	v_mov_b64_e32 v[138:139], s[46:47]
	v_add_u32_e32 v154, v4, v3
	v_add_u32_e32 v155, v4, v5
	s_mov_b32 s15, 0xa87000
	s_mov_b32 s16, 0xa89000
	s_mov_b32 s17, 0xa8b000
	s_mov_b64 s[2:3], 0x180
	s_mov_b64 s[4:5], 0xc000
	s_movk_i32 s18, 0x210
	v_and_b32_e32 v76, 63, v148
	v_lshrrev_b32_e32 v77, 6, v148
	v_and_b32_e32 v130, 31, v76
	v_lshlrev_b32_e32 v130, 6, v130
	v_lshrrev_b32_e32 v64, 5, v76
	v_bfe_u32 v65, v76, 2, 2
	v_xor_b32_e32 v64, v64, v65
	v_lshl_add_u32 v130, v64, 4, v130
	v_lshrrev_b32_e32 v64, 1, v77
	v_lshl_add_u32 v151, v64, 12, v130
	v_and_b32_e32 v64, 1, v77
	v_lshl_add_u32 v157, v64, 12, v130
	v_xor_b32_e32 v156, 32, v151
	v_xor_b32_e32 v164, 32, v157
	v_lshrrev_b32_e32 v130, 2, v76
	v_lshlrev_b32_e32 v130, 6, v130
	v_and_b32_e32 v64, 3, v76
	v_bfe_u32 v65, v76, 4, 2
	v_xor_b32_e32 v64, v64, v65
	v_lshl_add_u32 v130, v64, 4, v130
	v_lshl_add_u32 v165, v77, 11, v130
	v_lshrrev_b32_e32 v130, 2, v76
	v_lshl_add_u32 v130, v77, 5, v130
	v_mul_u32_u24_e32 v130, 0x2a00, v130
	v_and_b32_e32 v64, 3, v76
	v_bfe_u32 v65, v76, 4, 2
	v_xor_b32_e32 v64, v64, v65
	v_lshl_add_u32 v166, v64, 4, v130
	v_add_u32_e32 v167, 0x2a000, v166
	v_readfirstlane_b32 s28, v77
	s_lshl_b32 s28, s28, 11
	s_and_b32 s33, s8, 7
	s_lshr_b32 s8, s8, 3
	s_add_u32 s56, s9, 7
	s_sub_u32 s56, s56, s33
	s_lshr_b32 s56, s56, 3
	s_sub_u32 s57, 268, s33
	s_lshr_b32 s57, s57, 3
	s_mul_i32 s57, s57, 4
	s_branch .Lg2b_hdr

.Lg2b_ctl:
	s_cmp_eq_u32 s32, 0
	s_cbranch_scc1 .Lg2b_pass2
	s_add_i32 s8, s8, s56
	s_cmp_lt_u32 s8, s57
	s_cbranch_scc0 .LBB0_1224
	s_branch .Lg2b_hdr

.LBB0_1268:
	s_or_b64 exec, exec, s[2:3]
	v_mov_b32_e32 v88, v148
	s_mov_b32 s9, s55
	s_waitcnt lgkmcnt(0)
	s_barrier
	s_mov_b32 s16, s94
	s_cmpk_gt_i32 s9, 0x2cdb
	s_cbranch_scc1 .LBB0_1272
	v_ashrrev_i32_e32 v4, 2, v88
	v_lshlrev_b32_e32 v0, 5, v4
	v_ashrrev_i32_e32 v1, 31, v0
	v_lshlrev_b32_e32 v5, 4, v88
	v_readlane_b32 s0, v158, 28
	v_lshlrev_b64 v[0:1], 1, v[0:1]
	v_and_b32_e32 v72, 48, v5
	v_mov_b32_e32 v73, 0
	v_readlane_b32 s1, v158, 29
	s_movk_i32 s2, 0x50
	v_lshl_add_u64 v[2:3], s[44:45], 0, v[0:1]
	v_lshl_add_u64 v[0:1], s[0:1], 0, v[0:1]
	v_mad_u64_u32 v[78:79], s[0:1], v4, s2, v[72:73]
	v_lshl_add_u64 v[74:75], v[2:3], 0, v[72:73]
	v_lshl_add_u64 v[76:77], v[0:1], 0, v[72:73]
	v_lshrrev_b32_e32 v1, 1, v88
	v_and_b32_e32 v2, 31, v88
	s_mov_b32 s0, 0xfffffc0
	v_and_b32_e32 v0, 16, v1
	v_and_or_b32 v1, v1, s0, v2
	v_and_b32_e32 v2, 0x5f, v88
	v_mad_u64_u32 v[80:81], s[0:1], v1, s2, v[0:1]
	v_mad_u32_u24 v79, v2, s2, v0
	s_add_u32 s2, s90, 0x22aa00
	s_mov_b32 s0, 0x358637bd
	s_addc_u32 s3, s91, 0
	s_movk_i32 s17, 0x2000
	s_movk_i32 s18, 0x4000
	s_movk_i32 s19, 0x6000
	s_mov_b32 s20, 0x8000
	s_mov_b32 s21, 0xa000
	s_mov_b32 s22, 0xc000
	s_mov_b32 s23, 0xe000
	s_mov_b32 s24, 0x10000
	s_mov_b32 s25, 0x12000
	s_mov_b32 s26, 0x14000
	s_mov_b32 s27, 0x16000
	s_mov_b32 s28, 0x18000
	s_mov_b32 s29, 0x1a000
	s_mov_b32 s30, 0x1c000
	s_mov_b32 s31, 0x1e000
	s_mov_b32 s33, 0x20000
	s_mov_b32 s34, 0x22000
	s_mov_b32 s35, 0x24000
	s_mov_b32 s36, 0x26000
	s_mov_b32 s37, 0x28000
	s_mov_b32 s38, 0x2a000
	s_mov_b32 s39, 0x2c000
	s_mov_b32 s50, 0x2e000
	s_mov_b32 s51, 0x30000
	s_mov_b32 s52, 0x32000
	s_mov_b32 s53, 0x34000
	s_mov_b32 s54, 0x36000
	s_mov_b32 s55, 0x38000
	s_mov_b32 s56, 0x3a000
	s_mov_b32 s57, 0x3c000
	s_mov_b32 s58, 0x3e000
	s_mov_b32 s59, 0x3f000
	s_movk_i32 s60, 0xffc0
	s_movk_i32 s61, 0x90
	s_mov_b32 s8, 0x3a800000
	v_mov_b64_e32 v[82:83], s[0:1]
	s_mov_b32 s62, 0x800000
	s_movk_i32 s63, 0x58
	v_and_b32_e32 v72, 63, v148
	v_lshrrev_b32_e32 v73, 6, v148
	v_and_b32_e32 v146, 31, v72
	v_lshlrev_b32_e32 v146, 6, v146
	v_lshrrev_b32_e32 v147, 5, v72
	v_bfe_u32 v165, v72, 2, 2
	v_xor_b32_e32 v147, v147, v165
	v_lshl_add_u32 v146, v147, 4, v146
	v_lshrrev_b32_e32 v147, 1, v73
	v_lshl_add_u32 v160, v147, 12, v146
	v_and_b32_e32 v147, 1, v73
	v_lshl_add_u32 v162, v147, 12, v146
	v_xor_b32_e32 v161, 32, v160
	v_xor_b32_e32 v163, 32, v162
	v_lshrrev_b32_e32 v146, 2, v72
	v_lshlrev_b32_e32 v146, 6, v146
	v_and_b32_e32 v147, 3, v72
	v_bfe_u32 v165, v72, 4, 2
	v_xor_b32_e32 v147, v147, v165
	v_lshl_add_u32 v146, v147, 4, v146
	v_lshl_add_u32 v164, v73, 11, v146
	v_readfirstlane_b32 s24, v73
	s_lshl_b32 s24, s24, 11
	s_and_b32 s29, s9, 7
	s_lshr_b32 s9, s9, 3
	s_add_u32 s30, s16, 7
	s_sub_u32 s30, s30, s29
	s_lshr_b32 s30, s30, 3
	s_sub_u32 s31, 268, s29
	s_lshr_b32 s31, s31, 3
	s_mul_i32 s31, s31, 22
	s_branch .Lg3b_hdr

.Lg3b_ctl:
	s_cmp_eq_u32 s28, 0
	s_cbranch_scc1 .Lg3b_pass2
	s_add_i32 s9, s9, s30
	s_cmp_lt_u32 s9, s31
	s_cbranch_scc1 .Lg3b_hdr
	s_branch .Lg3b_exit

.LBB0_1316:
	s_or_b64 exec, exec, s[2:3]
	v_mov_b32_e32 v144, v148
	s_mov_b32 s8, s55
	s_waitcnt lgkmcnt(0)
	s_barrier
	s_mov_b32 s9, s94
	s_cmpk_gt_i32 s8, 0x827
	s_cbranch_scc1 .LBB0_1339
	s_waitcnt vmcnt(0)
	v_ashrrev_i32_e32 v8, 2, v144
	v_lshlrev_b32_e32 v0, 5, v8
	v_ashrrev_i32_e32 v1, 31, v0
	v_lshlrev_b64 v[2:3], 1, v[0:1]
	v_lshlrev_b32_e32 v0, 4, v144
	v_and_b32_e32 v6, 48, v0
	v_mov_b32_e32 v0, 0
	v_readlane_b32 s0, v158, 26
	v_lshl_add_u64 v[4:5], s[46:47], 0, v[2:3]
	v_mov_b32_e32 v7, v0
	v_readlane_b32 s1, v158, 27
	v_lshl_add_u64 v[132:133], v[4:5], 0, v[6:7]
	v_mov_b32_e32 v145, 0xb0000
	v_lshl_add_u64 v[4:5], s[0:1], 0, v[2:3]
	v_lshl_add_u64 v[134:135], v[4:5], 0, v[6:7]
	v_lshrrev_b32_e32 v4, 1, v144
	v_and_b32_e32 v7, 31, v144
	s_mov_b32 s1, 0xfffffc0
	s_movk_i32 s0, 0x50
	v_and_b32_e32 v5, 16, v4
	v_and_or_b32 v4, v4, s1, v7
	v_and_b32_e32 v7, 0x5f, v144
	v_mul_lo_u32 v1, v8, s0
	v_mul_lo_u32 v4, v4, s0
	v_mul_u32_u24_e32 v7, 0x50, v7
	v_or_b32_e32 v2, v2, v6
	v_lshl_add_u64 v[136:137], s[48:49], 0, v[2:3]
	s_movk_i32 s10, 0x2000
	s_movk_i32 s11, 0x4000
	s_movk_i32 s12, 0x5000
	v_add_u32_e32 v146, v1, v6
	v_add_u32_e32 v147, v5, v4
	v_add_u32_e32 v150, v5, v7
	s_movk_i32 s13, 0x7000
	s_mov_b32 s14, 0x1887000
	s_movk_i32 s15, 0x210
	v_and_b32_e32 v142, 63, v148
	v_lshrrev_b32_e32 v143, 6, v148
	v_and_b32_e32 v154, 31, v142
	v_lshlrev_b32_e32 v154, 6, v154
	v_lshrrev_b32_e32 v155, 5, v142
	v_bfe_u32 v156, v142, 2, 2
	v_xor_b32_e32 v155, v155, v156
	v_lshl_add_u32 v154, v155, 4, v154
	v_lshrrev_b32_e32 v155, 1, v143
	v_lshl_add_u32 v81, v155, 12, v154
	v_and_b32_e32 v155, 1, v143
	v_lshl_add_u32 v146, v155, 12, v154
	v_xor_b32_e32 v145, 32, v81
	v_xor_b32_e32 v147, 32, v146
	v_lshrrev_b32_e32 v154, 2, v142
	v_lshlrev_b32_e32 v154, 6, v154
	v_and_b32_e32 v155, 3, v142
	v_bfe_u32 v156, v142, 4, 2
	v_xor_b32_e32 v155, v155, v156
	v_lshl_add_u32 v154, v155, 4, v154
	v_lshl_add_u32 v157, v143, 11, v154
	v_readfirstlane_b32 s28, v143
	s_lshl_b32 s28, s28, 11
	s_and_b32 s33, s8, 7
	s_lshr_b32 s8, s8, 3
	s_add_u32 s56, s9, 7
	s_sub_u32 s56, s56, s33
	s_lshr_b32 s56, s56, 3
	s_sub_u32 s57, 268, s33
	s_lshr_b32 s57, s57, 3
	s_mul_i32 s57, s57, 4
	s_branch .Lg4b_hdr
